# baseline (speedup 1.0000x reference)
; #define LAS __attribute__((address_space(3)))
; #define MFMA32(a, b, c) __builtin_amdgcn_mfma_f32_32x32x16_bf16((a), (b), (c), 0, 0, 0)
; #define ATT_LOAD(kr, vr, t) do { const bf16_t* kp_ = KVb + (size_t)(t) * 64 * 2048 + kn_off; \
;         kr[0] = *(const u32x4*)kp_; kr[1] = *(const u32x4*)(kp_ + 32 * 2048); kr[2] = *(const u32x4*)(KPEb + (t) * 64 * 64 + kp_off); \
;         const bf16_t* vp_ = VTb + (t) * 64 + v_off; vr[0] = *(const u32x4*)vp_; vr[1] = *(const u32x4*)(vp_ + 64 * SEQ); } while (0)
; #define ATT_TILE(t, slot) do { const int rel_ = (t) - 4 * qb; if (rel_ <= (w >> 1)) { qk_softmax((t), (slot), rel_ == (w >> 1)); pv(slot); } } while (0)
; DI void attn_unit(const Params& P, LAS unsigned char* lds, int b, int h, int qb, bool dry) {
;     ...
;     auto qk_softmax = [&](int kt, int kslot, bool domask) {
;         const LAS unsigned char* kb_ = Ks + kslot * KS_BYTES + r * KS_STRIDE + 16 * hh;
;         f32x16 s0, s1;
;         __builtin_amdgcn_s_setprio(1);
;         { const f32x16 z16 = {0.f, 0.f, 0.f, 0.f, 0.f, 0.f, 0.f, 0.f, 0.f, 0.f, 0.f, 0.f, 0.f, 0.f, 0.f, 0.f};
;           const bf16x8 a0 = *(const LAS bf16x8*)(kb_), a1 = *(const LAS bf16x8*)(kb_ + 32 * KS_STRIDE);
;           s0 = MFMA32(a0, qf[0], z16); s1 = MFMA32(a1, qf[0], z16); }
; #pragma unroll
;         for (int s = 1; s < 12; ++s) {
;             const bf16x8 a0 = *(const LAS bf16x8*)(kb_ + 32 * s), a1 = *(const LAS bf16x8*)(kb_ + 32 * KS_STRIDE + 32 * s);
;             s0 = MFMA32(a0, qf[s], s0); s1 = MFMA32(a1, qf[s], s1);
;         }
;         __builtin_amdgcn_s_setprio(0);
;     ...
;     for (int kt = 0; kt < nt; kt += 2) {
;         const bool more2 = kt + 2 < nt;
;         if (more2) ATT_LOAD(kB, vB, kt + 2);
;         ATT_TILE(kt, 0);
.LBB0_33:
	s_cmp_lt_u32 s20, s59
	s_cselect_b64 s[52:53], -1, 0
	s_cmp_ge_u32 s20, s59
	s_cselect_b64 s[50:51], -1, 0
.LBB0_35:
	s_add_i32 s80, s62, s20
	s_add_i32 s40, s80, -2
	s_cmp_gt_i32 s40, s26
	v_add_u32_e32 v220, v213, v184
	s_cbranch_scc1 .LBB0_41
	s_add_i32 s40, s63, s20
	s_cmp_lg_u32 s40, 2
	s_setprio 1
	ds_read_b128 v[222:225], v220
	ds_read_b128 v[226:229], v220 offset:12800
	ds_read_b128 v[230:233], v220 offset:32
	ds_read_b128 v[234:237], v220 offset:12832
	s_waitcnt lgkmcnt(3)
	v_mfma_f32_32x32x16_bf16 v[80:95], v[222:225], v[96:99], v[196:211]
	ds_read_b128 v[222:225], v220 offset:64
	s_waitcnt lgkmcnt(3)
	v_mfma_f32_32x32x16_bf16 v[64:79], v[226:229], v[96:99], v[196:211]
	ds_read_b128 v[226:229], v220 offset:12864
	s_waitcnt lgkmcnt(3)
	v_mfma_f32_32x32x16_bf16 v[80:95], v[230:233], v[100:103], v[80:95]
	ds_read_b128 v[230:233], v220 offset:96
	s_waitcnt lgkmcnt(3)
	v_mfma_f32_32x32x16_bf16 v[64:79], v[234:237], v[100:103], v[64:79]
	ds_read_b128 v[234:237], v220 offset:12896
	s_waitcnt lgkmcnt(3)
	v_mfma_f32_32x32x16_bf16 v[80:95], v[222:225], v[104:107], v[80:95]
	ds_read_b128 v[222:225], v220 offset:128
	s_waitcnt lgkmcnt(3)
	v_mfma_f32_32x32x16_bf16 v[64:79], v[226:229], v[104:107], v[64:79]
	ds_read_b128 v[226:229], v220 offset:12928
	s_waitcnt lgkmcnt(3)
	v_mfma_f32_32x32x16_bf16 v[80:95], v[230:233], v[108:111], v[80:95]
	ds_read_b128 v[230:233], v220 offset:160
	s_waitcnt lgkmcnt(3)
	v_mfma_f32_32x32x16_bf16 v[64:79], v[234:237], v[108:111], v[64:79]
	ds_read_b128 v[234:237], v220 offset:12960
	s_waitcnt lgkmcnt(3)
	v_mfma_f32_32x32x16_bf16 v[80:95], v[222:225], v[112:115], v[80:95]
	ds_read_b128 v[222:225], v220 offset:192
	s_waitcnt lgkmcnt(3)
	v_mfma_f32_32x32x16_bf16 v[64:79], v[226:229], v[112:115], v[64:79]
	ds_read_b128 v[226:229], v220 offset:12992
	s_waitcnt lgkmcnt(3)
	v_mfma_f32_32x32x16_bf16 v[80:95], v[230:233], v[116:119], v[80:95]
	ds_read_b128 v[230:233], v220 offset:224
	s_waitcnt lgkmcnt(3)
	v_mfma_f32_32x32x16_bf16 v[64:79], v[234:237], v[116:119], v[64:79]
	ds_read_b128 v[234:237], v220 offset:13024
	s_waitcnt lgkmcnt(3)
	v_mfma_f32_32x32x16_bf16 v[80:95], v[222:225], v[120:123], v[80:95]
	ds_read_b128 v[222:225], v220 offset:256
	s_waitcnt lgkmcnt(3)
	v_mfma_f32_32x32x16_bf16 v[64:79], v[226:229], v[120:123], v[64:79]
	ds_read_b128 v[226:229], v220 offset:13056
	s_waitcnt lgkmcnt(3)
	v_mfma_f32_32x32x16_bf16 v[80:95], v[230:233], v[124:127], v[80:95]
	ds_read_b128 v[230:233], v220 offset:288
	s_waitcnt lgkmcnt(3)
	v_mfma_f32_32x32x16_bf16 v[64:79], v[234:237], v[124:127], v[64:79]
	ds_read_b128 v[234:237], v220 offset:13088
	s_waitcnt lgkmcnt(3)
	v_mfma_f32_32x32x16_bf16 v[80:95], v[222:225], v[128:131], v[80:95]
	ds_read_b128 v[222:225], v220 offset:320
	s_waitcnt lgkmcnt(3)
	v_mfma_f32_32x32x16_bf16 v[64:79], v[226:229], v[128:131], v[64:79]
	ds_read_b128 v[226:229], v220 offset:13120
	s_waitcnt lgkmcnt(3)
	v_mfma_f32_32x32x16_bf16 v[80:95], v[230:233], v[132:135], v[80:95]
	ds_read_b128 v[230:233], v220 offset:352
	s_waitcnt lgkmcnt(3)
	v_mfma_f32_32x32x16_bf16 v[64:79], v[234:237], v[132:135], v[64:79]
	ds_read_b128 v[234:237], v220 offset:13152
	s_waitcnt lgkmcnt(3)
	v_mfma_f32_32x32x16_bf16 v[80:95], v[222:225], v[136:139], v[80:95]
	s_waitcnt lgkmcnt(2)
	v_mfma_f32_32x32x16_bf16 v[64:79], v[226:229], v[136:139], v[64:79]
	s_waitcnt lgkmcnt(1)
	v_mfma_f32_32x32x16_bf16 v[80:95], v[230:233], v[140:143], v[80:95]
	s_waitcnt lgkmcnt(0)
	v_mfma_f32_32x32x16_bf16 v[64:79], v[234:237], v[140:143], v[64:79]
	s_setprio 0
	s_nop 0
	s_mov_b64 vcc, s[52:53]
	s_cbranch_vccnz .Lattn_hw0_v5
	s_waitcnt vmcnt(0)
	s_branch .Lattn_hw0_go

; #define ATT_LOAD(kr, vr, t) do { const bf16_t* kp_ = KVb + (size_t)(t) * 64 * 2048 + kn_off; \
;         kr[0] = *(const u32x4*)kp_; kr[1] = *(const u32x4*)(kp_ + 32 * 2048); kr[2] = *(const u32x4*)(KPEb + (t) * 64 * 64 + kp_off); \
;         const bf16_t* vp_ = VTb + (t) * 64 + v_off; vr[0] = *(const u32x4*)vp_; vr[1] = *(const u32x4*)(vp_ + 64 * SEQ); } while (0)
; #define ATT_TILE(t, slot) do { const int rel_ = (t) - 4 * qb; if (rel_ <= (w >> 1)) { qk_softmax((t), (slot), rel_ == (w >> 1)); pv(slot); } } while (0)
; DI void attn_unit(const Params& P, LAS unsigned char* lds, int b, int h, int qb, bool dry) {
;     ...
;         ATT_STORE(kA, vA, 1);
;         __syncthreads();
;         if (more2) ATT_LOAD(kA, vA, kt + 3);
;         ATT_TILE(kt + 1, 1);
.Lattn_pfA1_skip:
	s_barrier
	s_add_i32 s80, s80, -1
	s_cmp_gt_i32 s80, s26
	s_cbranch_scc0 .LBB0_45

; #define LAS __attribute__((address_space(3)))
; #define MFMA32(a, b, c) __builtin_amdgcn_mfma_f32_32x32x16_bf16((a), (b), (c), 0, 0, 0)
; #define ATT_LOAD(kr, vr, t) do { const bf16_t* kp_ = KVb + (size_t)(t) * 64 * 2048 + kn_off; \
;         kr[0] = *(const u32x4*)kp_; kr[1] = *(const u32x4*)(kp_ + 32 * 2048); kr[2] = *(const u32x4*)(KPEb + (t) * 64 * 64 + kp_off); \
;         const bf16_t* vp_ = VTb + (t) * 64 + v_off; vr[0] = *(const u32x4*)vp_; vr[1] = *(const u32x4*)(vp_ + 64 * SEQ); } while (0)
; #define ATT_TILE(t, slot) do { const int rel_ = (t) - 4 * qb; if (rel_ <= (w >> 1)) { qk_softmax((t), (slot), rel_ == (w >> 1)); pv(slot); } } while (0)
; DI void attn_unit(const Params& P, LAS unsigned char* lds, int b, int h, int qb, bool dry) {
;     ...
;     auto qk_softmax = [&](int kt, int kslot, bool domask) {
;         const LAS unsigned char* kb_ = Ks + kslot * KS_BYTES + r * KS_STRIDE + 16 * hh;
;         f32x16 s0, s1;
;         __builtin_amdgcn_s_setprio(1);
;         { const f32x16 z16 = {0.f, 0.f, 0.f, 0.f, 0.f, 0.f, 0.f, 0.f, 0.f, 0.f, 0.f, 0.f, 0.f, 0.f, 0.f, 0.f};
;           const bf16x8 a0 = *(const LAS bf16x8*)(kb_), a1 = *(const LAS bf16x8*)(kb_ + 32 * KS_STRIDE);
;           s0 = MFMA32(a0, qf[0], z16); s1 = MFMA32(a1, qf[0], z16); }
; #pragma unroll
;         for (int s = 1; s < 12; ++s) {
;             const bf16x8 a0 = *(const LAS bf16x8*)(kb_ + 32 * s), a1 = *(const LAS bf16x8*)(kb_ + 32 * KS_STRIDE + 32 * s);
;             s0 = MFMA32(a0, qf[s], s0); s1 = MFMA32(a1, qf[s], s1);
;         }
;         __builtin_amdgcn_s_setprio(0);
;     ...
;     for (int kt = 0; kt < nt; kt += 2) {
;         const bool more2 = kt + 2 < nt;
;         if (more2) ATT_LOAD(kB, vB, kt + 2);
;         ATT_TILE(kt, 0);
.LBB0_53:
	s_cmp_lt_u32 s20, s35
	s_cselect_b64 s[30:31], -1, 0
	s_cmp_ge_u32 s20, s35
	s_cselect_b64 s[2:3], -1, 0
.LBB0_55:
	s_add_i32 s37, s52, s20
	s_add_i32 s40, s37, -2
	s_cmp_gt_i32 s40, s36
	v_add_u32_e32 v220, v213, v184
	s_cbranch_scc1 .LBB0_61
	s_add_i32 s40, s27, s20
	s_cmp_lg_u32 s40, 2
	s_setprio 1
	ds_read_b128 v[222:225], v220
	ds_read_b128 v[226:229], v220 offset:12800
	ds_read_b128 v[230:233], v220 offset:32
	ds_read_b128 v[234:237], v220 offset:12832
	s_waitcnt lgkmcnt(3)
	v_mfma_f32_32x32x16_bf16 v[80:95], v[222:225], v[96:99], v[196:211]
	ds_read_b128 v[222:225], v220 offset:64
	s_waitcnt lgkmcnt(3)
	v_mfma_f32_32x32x16_bf16 v[64:79], v[226:229], v[96:99], v[196:211]
	ds_read_b128 v[226:229], v220 offset:12864
	s_waitcnt lgkmcnt(3)
	v_mfma_f32_32x32x16_bf16 v[80:95], v[230:233], v[100:103], v[80:95]
	ds_read_b128 v[230:233], v220 offset:96
	s_waitcnt lgkmcnt(3)
	v_mfma_f32_32x32x16_bf16 v[64:79], v[234:237], v[100:103], v[64:79]
	ds_read_b128 v[234:237], v220 offset:12896
	s_waitcnt lgkmcnt(3)
	v_mfma_f32_32x32x16_bf16 v[80:95], v[222:225], v[104:107], v[80:95]
	ds_read_b128 v[222:225], v220 offset:128
	s_waitcnt lgkmcnt(3)
	v_mfma_f32_32x32x16_bf16 v[64:79], v[226:229], v[104:107], v[64:79]
	ds_read_b128 v[226:229], v220 offset:12928
	s_waitcnt lgkmcnt(3)
	v_mfma_f32_32x32x16_bf16 v[80:95], v[230:233], v[108:111], v[80:95]
	ds_read_b128 v[230:233], v220 offset:160
	s_waitcnt lgkmcnt(3)
	v_mfma_f32_32x32x16_bf16 v[64:79], v[234:237], v[108:111], v[64:79]
	ds_read_b128 v[234:237], v220 offset:12960
	s_waitcnt lgkmcnt(3)
	v_mfma_f32_32x32x16_bf16 v[80:95], v[222:225], v[112:115], v[80:95]
	ds_read_b128 v[222:225], v220 offset:192
	s_waitcnt lgkmcnt(3)
	v_mfma_f32_32x32x16_bf16 v[64:79], v[226:229], v[112:115], v[64:79]
	ds_read_b128 v[226:229], v220 offset:12992
	s_waitcnt lgkmcnt(3)
	v_mfma_f32_32x32x16_bf16 v[80:95], v[230:233], v[116:119], v[80:95]
	ds_read_b128 v[230:233], v220 offset:224
	s_waitcnt lgkmcnt(3)
	v_mfma_f32_32x32x16_bf16 v[64:79], v[234:237], v[116:119], v[64:79]
	ds_read_b128 v[234:237], v220 offset:13024
	s_waitcnt lgkmcnt(3)
	v_mfma_f32_32x32x16_bf16 v[80:95], v[222:225], v[120:123], v[80:95]
	ds_read_b128 v[222:225], v220 offset:256
	s_waitcnt lgkmcnt(3)
	v_mfma_f32_32x32x16_bf16 v[64:79], v[226:229], v[120:123], v[64:79]
	ds_read_b128 v[226:229], v220 offset:13056
	s_waitcnt lgkmcnt(3)
	v_mfma_f32_32x32x16_bf16 v[80:95], v[230:233], v[124:127], v[80:95]
	ds_read_b128 v[230:233], v220 offset:288
	s_waitcnt lgkmcnt(3)
	v_mfma_f32_32x32x16_bf16 v[64:79], v[234:237], v[124:127], v[64:79]
	ds_read_b128 v[234:237], v220 offset:13088
	s_waitcnt lgkmcnt(3)
	v_mfma_f32_32x32x16_bf16 v[80:95], v[222:225], v[128:131], v[80:95]
	ds_read_b128 v[222:225], v220 offset:320
	s_waitcnt lgkmcnt(3)
	v_mfma_f32_32x32x16_bf16 v[64:79], v[226:229], v[128:131], v[64:79]
	ds_read_b128 v[226:229], v220 offset:13120
	s_waitcnt lgkmcnt(3)
	v_mfma_f32_32x32x16_bf16 v[80:95], v[230:233], v[132:135], v[80:95]
	ds_read_b128 v[230:233], v220 offset:352
	s_waitcnt lgkmcnt(3)
	v_mfma_f32_32x32x16_bf16 v[64:79], v[234:237], v[132:135], v[64:79]
	ds_read_b128 v[234:237], v220 offset:13152
	s_waitcnt lgkmcnt(3)
	v_mfma_f32_32x32x16_bf16 v[80:95], v[222:225], v[136:139], v[80:95]
	s_waitcnt lgkmcnt(2)
	v_mfma_f32_32x32x16_bf16 v[64:79], v[226:229], v[136:139], v[64:79]
	s_waitcnt lgkmcnt(1)
	v_mfma_f32_32x32x16_bf16 v[80:95], v[230:233], v[140:143], v[80:95]
	s_waitcnt lgkmcnt(0)
	v_mfma_f32_32x32x16_bf16 v[64:79], v[234:237], v[140:143], v[64:79]
	s_setprio 0
	s_nop 0
	s_mov_b64 vcc, s[30:31]
	s_cbranch_vccnz .Lattn_hw2_v5
	s_waitcnt vmcnt(0)
	s_branch .Lattn_hw2_go

; #define ATT_LOAD(kr, vr, t) do { const bf16_t* kp_ = KVb + (size_t)(t) * 64 * 2048 + kn_off; \
;         kr[0] = *(const u32x4*)kp_; kr[1] = *(const u32x4*)(kp_ + 32 * 2048); kr[2] = *(const u32x4*)(KPEb + (t) * 64 * 64 + kp_off); \
;         const bf16_t* vp_ = VTb + (t) * 64 + v_off; vr[0] = *(const u32x4*)vp_; vr[1] = *(const u32x4*)(vp_ + 64 * SEQ); } while (0)
; #define ATT_TILE(t, slot) do { const int rel_ = (t) - 4 * qb; if (rel_ <= (w >> 1)) { qk_softmax((t), (slot), rel_ == (w >> 1)); pv(slot); } } while (0)
; DI void attn_unit(const Params& P, LAS unsigned char* lds, int b, int h, int qb, bool dry) {
;     ...
;         ATT_STORE(kA, vA, 1);
;         __syncthreads();
;         if (more2) ATT_LOAD(kA, vA, kt + 3);
;         ATT_TILE(kt + 1, 1);
.Lattn_pfA2_skip:
	s_barrier
	s_add_i32 s37, s37, -1
	s_cmp_gt_i32 s37, s36
	s_cbranch_scc0 .LBB0_65
